# speedup vs baseline: 1.0084x; 1.0084x over previous
; DEV void phase_attn(const Params& p, unsigned char* smem) {
;     ...
;   for (int it = blockIdx.x; it < nitem; it += gridDim.x) {
;     int b, kvh, q0, row0;
;     bool lat = it < 2048;
;     if (lat) { b = it >> 10; kvh = (it >> 8) & 3; q0 = (it & 255) * 32; row0 = b * 8192 + q0; }
;     else { int i2 = it - 2048; b = i2 >> 5; kvh = (i2 >> 3) & 3; q0 = (i2 & 7) * 32; row0 = NLAT + b * 256 + q0; }
.LBB0_278:
	s_andn2_b64 vcc, exec, s[10:11]
	s_cbranch_vccnz .LBB0_280
	s_and_b32 s4, s31, 7
	s_lshl_b32 s4, s4, 8
	s_lshr_b32 s10, s31, 3
	s_add_i32 s35, s4, s10
	s_ashr_i32 s4, s35, 10
	s_lshl_b32 s10, s35, 5
	s_and_b32 s38, s10, 0x1fe0
	s_lshl_b32 s18, s4, 13
	s_lshl_b32 s4, s4, 8
	s_lshr_b32 s34, s35, 8
	s_or_b32 s35, s18, s38
	s_add_i32 s19, s4, 0x4000
